# warm: seam L2 warm-up - idle waves 1-4 touch the next GEMM phase's first weight K-tiles with scalar loads during the S2/S5/S8 waits
# baseline (speedup 1.0000x reference)
.Llb_acq_s2:
	s_waitcnt vmcnt(0)
	s_branch .Llb_done_s2
.Lwarm_s2:
	v_readfirstlane_b32 s98, v0
	s_lshr_b32 s98, s98, 6
	s_add_i32 s98, s98, -1
	s_cmp_gt_u32 s98, 3
	s_cbranch_scc1 .Llb_done_s2
	s_lshl_b32 s98, s98, 6
	s_lshr_b32 s99, s24, 6
	s_lshl_b32 s99, s99, 8
	s_add_i32 s98, s98, s99
	s_mul_i32 s98, s98, 0xb00
	v_readlane_b32 s8, v254, 12
	v_readlane_b32 s9, v254, 13
	s_add_u32 s8, s8, 0x12fc000
	s_addc_u32 s9, s9, 0
	s_add_u32 s8, s8, s98
	s_addc_u32 s9, s9, 0
	s_movk_i32 s99, 64
.Lwarm_loop_s2:
	s_load_dword s98, s[8:9], 0x0
	s_load_dword s98, s[8:9], 0x80
	s_add_u32 s8, s8, 0xb00
	s_addc_u32 s9, s9, 0
	s_add_i32 s99, s99, -1
	s_cmp_lg_u32 s99, 0
	s_cbranch_scc1 .Lwarm_loop_s2

.Lwarm_s5:
	v_readfirstlane_b32 s98, v0
	s_lshr_b32 s98, s98, 6
	s_add_i32 s98, s98, -1
	s_cmp_gt_u32 s98, 3
	s_cbranch_scc1 .Llb_done_s5
	s_lshl_b32 s98, s98, 6
	s_lshr_b32 s99, s24, 6
	s_lshl_b32 s99, s99, 8
	s_add_i32 s98, s98, s99
	s_mul_i32 s98, s98, 0x800
	v_readlane_b32 s8, v254, 12
	v_readlane_b32 s9, v254, 13
	s_add_u32 s8, s8, 0x1cfc000
	s_addc_u32 s9, s9, 0
	s_add_u32 s8, s8, s98
	s_addc_u32 s9, s9, 0
	s_movk_i32 s99, 64
.Lwarm_loop_s5:
	s_load_dword s98, s[8:9], 0x0
	s_load_dword s98, s[8:9], 0x80
	s_add_u32 s8, s8, 0x800
	s_addc_u32 s9, s9, 0
	s_add_i32 s99, s99, -1
	s_cmp_lg_u32 s99, 0
	s_cbranch_scc1 .Lwarm_loop_s5

.Lwarm_s8:
	v_readfirstlane_b32 s98, v0
	s_lshr_b32 s98, s98, 6
	s_add_i32 s98, s98, -1
	s_cmp_gt_u32 s98, 3
	s_cbranch_scc1 .Llb_done_s8
	s_lshl_b32 s98, s98, 6
	s_lshr_b32 s99, s24, 6
	s_lshl_b32 s99, s99, 8
	s_add_i32 s98, s98, s99
	s_mul_i32 s98, s98, 0xb00
	v_readlane_b32 s8, v254, 12
	v_readlane_b32 s9, v254, 13
	s_add_u32 s8, s8, 0x29fc000
	s_addc_u32 s9, s9, 0
	s_add_u32 s8, s8, s98
	s_addc_u32 s9, s9, 0
	s_movk_i32 s99, 64
